# batched ss row-stat loads in w_in/uq epilogues; prologue: row loads issued together, weight-convert gain multiply deferred so loads stay in flight
# speedup vs baseline: 1.0331x; 1.0331x over previous
;     DI void operator()(const f32x4 (&acc)[2][2][4][2], const Unit& u, int wr, int wc, int fr, int fq) const {
;         const int row0 = u.pm * BM + wr * 64 + fr, col0 = u.pn * BM + wc * 32 + 8 * fq;
;         float ssv[2][4];
; #pragma unroll
;         for (int ai = 0; ai < 2; ++ai)
; #pragma unroll
;             for (int m = 0; m < 4; ++m) ssv[ai][m] = ss ? ss[row0 + ai * HALF + m * 16] : 0.f;
; #pragma unroll
;         for (int ai = 0; ai < 2; ++ai)
; #pragma unroll
;             for (int m = 0; m < 4; ++m) {
;                 const int r = row0 + ai * HALF + m * 16;
;                 const float rs = ss ? __builtin_amdgcn_rsqf(ssv[ai][m] * inv_dim + EPS) : 1.f;
.LBB0_368:
	s_lshl_b32 s1, s1, 8
	v_mov_b32_e32 v144, v202
	s_add_i32 s1, s1, s49
	v_cndmask_b32_e64 v141, 0, 1, s[26:27]
	v_and_or_b32 v140, v144, 15, s1
	v_mov_b32_e32 v157, 0x358637bd
	v_cmp_ne_u32_e64 s[6:7], 1, v141
	s_andn2_b64 vcc, exec, s[26:27]
	v_ashrrev_i32_e32 v141, 31, v140
	v_mov_b32_e32 v145, 0x358637bd
	s_cbranch_vccnz .LBB0_415
	v_lshl_add_u64 v[142:143], v[140:141], 2, s[22:23]
	global_load_dword v145, v[142:143], off
	global_load_dword v157, v[142:143], off offset:64
	global_load_dword v156, v[142:143], off offset:128
	global_load_dword v155, v[142:143], off offset:192
	global_load_dword v154, v[142:143], off offset:512
	global_load_dword v153, v[142:143], off offset:576
	global_load_dword v152, v[142:143], off offset:640
	global_load_dword v150, v[142:143], off offset:704
	s_waitcnt vmcnt(0)
	v_fmamk_f32 v145, v145, 0x3b2aaaab, v252
	v_fmamk_f32 v157, v157, 0x3b2aaaab, v252
	v_fmamk_f32 v156, v156, 0x3b2aaaab, v252
	v_fmamk_f32 v155, v155, 0x3b2aaaab, v252
	v_fmamk_f32 v154, v154, 0x3b2aaaab, v252
	v_fmamk_f32 v153, v153, 0x3b2aaaab, v252
	v_fmamk_f32 v152, v152, 0x3b2aaaab, v252
	v_fmamk_f32 v150, v150, 0x3b2aaaab, v252
	s_branch .LBB0_380

;     DI void operator()(const f32x4 (&acc)[2][2][4][2], const Unit& u, int wr, int wc, int fr, int fq) const {
;         const int row0 = u.pm * BM + wr * 64 + fr, col0 = u.pn * BM + wc * 32 + 8 * fq;
;         float ssv[2][4];
; #pragma unroll
;         for (int ai = 0; ai < 2; ++ai)
; #pragma unroll
;             for (int m = 0; m < 4; ++m) ssv[ai][m] = ss ? ss[row0 + ai * HALF + m * 16] : 0.f;
; #pragma unroll
;         for (int ai = 0; ai < 2; ++ai)
; #pragma unroll
;             for (int m = 0; m < 4; ++m) {
;                 const int r = row0 + ai * HALF + m * 16;
;                 const float rs = ss ? __builtin_amdgcn_rsqf(ssv[ai][m] * inv_dim + EPS) : 1.f;
.LBB0_436:
	s_lshl_b32 s1, s1, 8
	v_mov_b32_e32 v144, v202
	s_add_i32 s1, s1, s59
	v_cndmask_b32_e64 v141, 0, 1, s[30:31]
	v_and_or_b32 v140, v144, 15, s1
	v_mov_b32_e32 v157, 0x358637bd
	v_cmp_ne_u32_e64 s[6:7], 1, v141
	s_andn2_b64 vcc, exec, s[30:31]
	v_ashrrev_i32_e32 v141, 31, v140
	v_mov_b32_e32 v145, 0x358637bd
	s_cbranch_vccnz .LBB0_531
	v_lshl_add_u64 v[142:143], v[140:141], 2, s[26:27]
	global_load_dword v145, v[142:143], off
	global_load_dword v157, v[142:143], off offset:64
	global_load_dword v156, v[142:143], off offset:128
	global_load_dword v155, v[142:143], off offset:192
	global_load_dword v154, v[142:143], off offset:512
	global_load_dword v153, v[142:143], off offset:576
	global_load_dword v152, v[142:143], off offset:640
	global_load_dword v150, v[142:143], off offset:704
	s_waitcnt vmcnt(0)
	v_fmamk_f32 v145, v145, 0x3a800000, v252
	v_fmamk_f32 v157, v157, 0x3a800000, v252
	v_fmamk_f32 v156, v156, 0x3a800000, v252
	v_fmamk_f32 v155, v155, 0x3a800000, v252
	v_fmamk_f32 v154, v154, 0x3a800000, v252
	v_fmamk_f32 v153, v153, 0x3a800000, v252
	v_fmamk_f32 v152, v152, 0x3a800000, v252
	v_fmamk_f32 v150, v150, 0x3a800000, v252
	s_branch .LBB0_448

; DI unsigned pk2(float lo, float hi) { f32x2_t v = {lo, hi}; bf16x2_t b = __builtin_convertvector(v, bf16x2_t); return __builtin_bit_cast(unsigned, b); }
; DI int ltid() { int t = threadIdx.x; asm volatile("" : "+v"(t)); return t; }
; DI void rows_to_bf16(const float* src, bf16_t* dst, float* ss, int nrows, int gw, int nw) {
;     const int lane = ltid() & 63;
;     for (int r = gw; r < nrows; r += nw) {
;         float q = 0.f;
; #pragma unroll
;         for (int i = 0; i < 4; ++i) {
;             const f32x4 v = *(const f32x4*)(src + (size_t)r * 1024 + i * 256 + lane * 4);
;             q += v[0] * v[0] + v[1] * v[1] + v[2] * v[2] + v[3] * v[3];
;             u32x2 w; w.x = pk2(v[0], v[1]); w.y = pk2(v[2], v[3]);
;             *(u32x2*)(dst + (size_t)r * 1024 + i * 256 + lane * 4) = w;
;         }
;         q = wave_sum(q);
;         if (lane == 0) ss[r] = q;
;     }
; }
.LBB0_634:
	s_waitcnt lgkmcnt(0)
	global_load_dwordx4 v[18:21], v[10:11], off offset:-3072
	global_load_dwordx4 v[22:25], v[10:11], off offset:-2048
	global_load_dwordx4 v[26:29], v[10:11], off offset:-1024
	global_load_dwordx4 v[30:33], v[10:11], off
	v_readlane_b32 s0, v254, 61
	v_readlane_b32 s1, v254, 62
	s_nop 1
	v_lshl_add_u64 v[36:37], s[0:1], 0, v[8:9]
	s_mov_b32 s0, 0xe29000
	v_add_co_u32_e32 v34, vcc, s0, v36
	s_nop 1
	v_addc_co_u32_e32 v35, vcc, 0, v37, vcc
	s_waitcnt vmcnt(3)
	v_mul_f32_e32 v17, v19, v19
	v_cvt_pk_bf16_f32 v36, v18, v19
	v_cvt_pk_bf16_f32 v37, v20, v21
	global_store_dwordx2 v[34:35], v[36:37], off offset:512
	v_fmac_f32_e32 v17, v18, v18
	v_fmac_f32_e32 v17, v20, v20
	v_fmac_f32_e32 v17, v21, v21
	s_waitcnt vmcnt(3)
	v_cvt_pk_bf16_f32 v38, v22, v23
	v_cvt_pk_bf16_f32 v39, v24, v25
	global_store_dwordx2 v[34:35], v[38:39], off offset:1024
	v_mul_f32_e32 v18, v23, v23
	v_fmac_f32_e32 v18, v22, v22
	v_fmac_f32_e32 v18, v24, v24
	v_fmac_f32_e32 v18, v25, v25
	v_add_f32_e32 v17, v17, v18
	s_waitcnt vmcnt(3)
	v_cvt_pk_bf16_f32 v40, v26, v27
	v_cvt_pk_bf16_f32 v41, v28, v29
	global_store_dwordx2 v[34:35], v[40:41], off offset:1536
	v_mul_f32_e32 v18, v27, v27
	v_fmac_f32_e32 v18, v26, v26
	v_fmac_f32_e32 v18, v28, v28
	v_fmac_f32_e32 v18, v29, v29
	v_add_f32_e32 v17, v17, v18
	s_waitcnt vmcnt(3)
	v_mul_f32_e32 v18, v31, v31
	v_fmac_f32_e32 v18, v30, v30
	v_fmac_f32_e32 v18, v32, v32
	v_fmac_f32_e32 v18, v33, v33
	v_add_f32_e32 v17, v17, v18
	ds_bpermute_b32 v18, v0, v17
	v_cvt_pk_bf16_f32 v20, v30, v31
	v_cvt_pk_bf16_f32 v21, v32, v33
	global_store_dwordx2 v[34:35], v[20:21], off offset:2048
	s_waitcnt lgkmcnt(0)
	v_add_f32_e32 v17, v17, v18
	ds_bpermute_b32 v18, v3, v17
	s_waitcnt lgkmcnt(0)
	v_add_f32_e32 v17, v17, v18
	ds_bpermute_b32 v18, v12, v17
	s_waitcnt lgkmcnt(0)
	v_add_f32_e32 v17, v17, v18
	ds_bpermute_b32 v18, v13, v17
	s_waitcnt lgkmcnt(0)
	v_add_f32_e32 v17, v17, v18
	ds_bpermute_b32 v18, v14, v17
	s_waitcnt lgkmcnt(0)
	v_add_f32_e32 v17, v17, v18
	ds_bpermute_b32 v18, v15, v17
	s_and_saveexec_b64 s[20:21], s[6:7]
	s_cbranch_execz .LBB0_633
	v_readlane_b32 s0, v254, 61
	v_readlane_b32 s1, v254, 62
	s_waitcnt lgkmcnt(0)
	v_add_f32_e32 v17, v17, v18
	v_lshl_add_u64 v[18:19], s[0:1], 0, v[6:7]
	global_store_dword v[18:19], v17, off
	s_branch .LBB0_633

; DI unsigned pk2(float lo, float hi) { f32x2_t v = {lo, hi}; bf16x2_t b = __builtin_convertvector(v, bf16x2_t); return __builtin_bit_cast(unsigned, b); }
; DI int ltid() { int t = threadIdx.x; asm volatile("" : "+v"(t)); return t; }
; DI void rows_to_bf16(const float* src, bf16_t* dst, float* ss, int nrows, int gw, int nw) {
;     const int lane = ltid() & 63;
;     for (int r = gw; r < nrows; r += nw) {
;         float q = 0.f;
; #pragma unroll
;         for (int i = 0; i < 4; ++i) {
;             const f32x4 v = *(const f32x4*)(src + (size_t)r * 1024 + i * 256 + lane * 4);
;             q += v[0] * v[0] + v[1] * v[1] + v[2] * v[2] + v[3] * v[3];
;             u32x2 w; w.x = pk2(v[0], v[1]); w.y = pk2(v[2], v[3]);
;             *(u32x2*)(dst + (size_t)r * 1024 + i * 256 + lane * 4) = w;
;         }
;         q = wave_sum(q);
;         if (lane == 0) ss[r] = q;
;     }
; }
.LBB0_639:
	s_waitcnt lgkmcnt(0)
	global_load_dwordx4 v[16:19], v[10:11], off offset:-3072
	global_load_dwordx4 v[20:23], v[10:11], off offset:-2048
	global_load_dwordx4 v[24:27], v[10:11], off offset:-1024
	global_load_dwordx4 v[28:31], v[10:11], off
	v_readlane_b32 s0, v254, 61
	v_readlane_b32 s1, v254, 62
	s_nop 1
	v_lshl_add_u64 v[36:37], s[0:1], 0, v[8:9]
	s_mov_b32 s0, 0x229000
	v_add_co_u32_e32 v32, vcc, s0, v36
	s_nop 1
	v_addc_co_u32_e32 v33, vcc, 0, v37, vcc
	s_waitcnt vmcnt(3)
	v_mul_f32_e32 v5, v17, v17
	v_cvt_pk_bf16_f32 v36, v16, v17
	v_cvt_pk_bf16_f32 v37, v18, v19
	global_store_dwordx2 v[32:33], v[36:37], off offset:512
	v_fmac_f32_e32 v5, v16, v16
	v_fmac_f32_e32 v5, v18, v18
	v_fmac_f32_e32 v5, v19, v19
	s_waitcnt vmcnt(3)
	v_cvt_pk_bf16_f32 v38, v20, v21
	v_cvt_pk_bf16_f32 v39, v22, v23
	global_store_dwordx2 v[32:33], v[38:39], off offset:1024
	v_mul_f32_e32 v16, v21, v21
	v_fmac_f32_e32 v16, v20, v20
	v_fmac_f32_e32 v16, v22, v22
	v_fmac_f32_e32 v16, v23, v23
	v_add_f32_e32 v5, v5, v16
	s_waitcnt vmcnt(3)
	v_cvt_pk_bf16_f32 v40, v24, v25
	v_cvt_pk_bf16_f32 v41, v26, v27
	global_store_dwordx2 v[32:33], v[40:41], off offset:1536
	v_mul_f32_e32 v16, v25, v25
	v_fmac_f32_e32 v16, v24, v24
	v_fmac_f32_e32 v16, v26, v26
	v_fmac_f32_e32 v16, v27, v27
	v_add_f32_e32 v5, v5, v16
	s_waitcnt vmcnt(3)
	v_mul_f32_e32 v16, v29, v29
	v_fmac_f32_e32 v16, v28, v28
	v_fmac_f32_e32 v16, v30, v30
	v_fmac_f32_e32 v16, v31, v31
	v_add_f32_e32 v5, v5, v16
	ds_bpermute_b32 v16, v0, v5
	v_cvt_pk_bf16_f32 v18, v28, v29
	v_cvt_pk_bf16_f32 v19, v30, v31
	global_store_dwordx2 v[32:33], v[18:19], off offset:2048
	s_waitcnt lgkmcnt(0)
	v_add_f32_e32 v5, v5, v16
	ds_bpermute_b32 v16, v3, v5
	s_waitcnt lgkmcnt(0)
	v_add_f32_e32 v5, v5, v16
	ds_bpermute_b32 v16, v12, v5
	s_waitcnt lgkmcnt(0)
	v_add_f32_e32 v5, v5, v16
	ds_bpermute_b32 v16, v13, v5
	s_waitcnt lgkmcnt(0)
	v_add_f32_e32 v5, v5, v16
	ds_bpermute_b32 v16, v14, v5
	s_waitcnt lgkmcnt(0)
	v_add_f32_e32 v5, v5, v16
	ds_bpermute_b32 v16, v15, v5
	s_and_saveexec_b64 s[20:21], s[6:7]
	s_cbranch_execz .LBB0_638
	v_readlane_b32 s0, v254, 61
	v_readlane_b32 s1, v254, 62
	s_waitcnt lgkmcnt(0)
	v_add_f32_e32 v5, v5, v16
	v_lshl_add_u64 v[16:17], s[0:1], 0, v[6:7]
	global_store_dword v[16:17], v5, off
	s_branch .LBB0_638

; DI int convert_weight(LAS unsigned char* lds, const WDesc d, int G, int bid, int goff) {
;     ...
;     for (int t0 = g0 * 4; t0 < ntile; t0 += G * 4) {
;         float v[4][8];
; #pragma unroll
;         for (int j = 0; j < 4; ++j) {
;             const int t = t0 + j, tc = t / nkt, tk = t % nkt;
;             const int cc = tid & 63, c = tc * 64 + cc;
;             int col; const float* src = d.s0;
;             if (d.map == 0) col = c;
;             else if (d.map == 1) { col = (c >> 8) * 128 + (c & 127); if (c & 128) src = d.s1; }
;             else { col = c < 2080 ? c : (c < 2304 ? -1 : c - 224); }
; #pragma unroll
;             for (int i = 0; i < 8; ++i) {
;                 const int kk = (tid >> 6) + 8 * i, k = tk * 64 + kk;
;                 float x = 0.f;
;                 if (t < ntile && col >= 0 && k < d.ksrc) { x = src[(size_t)k * d.ldsrc + col]; if (d.gain) x *= d.gain[k]; }
;                 v[j][i] = x;
.LBB0_706:
	v_mov_b32_e32 v64, 1.0
	v_mov_b32_e32 v65, 1.0
	v_mov_b32_e32 v66, 1.0
	v_mov_b32_e32 v67, 1.0
	v_mov_b32_e32 v68, 1.0
	v_mov_b32_e32 v69, 1.0
	v_mov_b32_e32 v70, 1.0
	v_mov_b32_e32 v71, 1.0
	v_mov_b32_e32 v72, 1.0
	v_mov_b32_e32 v73, 1.0
	v_mov_b32_e32 v74, 1.0
	v_mov_b32_e32 v75, 1.0
	v_mov_b32_e32 v76, 1.0
	v_mov_b32_e32 v77, 1.0
	v_mov_b32_e32 v78, 1.0
	v_mov_b32_e32 v79, 1.0
	v_mov_b32_e32 v80, 1.0
	v_mov_b32_e32 v81, 1.0
	v_mov_b32_e32 v82, 1.0
	v_mov_b32_e32 v83, 1.0
	v_mov_b32_e32 v84, 1.0
	v_mov_b32_e32 v85, 1.0
	v_mov_b32_e32 v86, 1.0
	v_mov_b32_e32 v87, 1.0
	v_mov_b32_e32 v88, 1.0
	v_mov_b32_e32 v89, 1.0
	v_mov_b32_e32 v90, 1.0
	v_mov_b32_e32 v91, 1.0
	v_mov_b32_e32 v92, 1.0
	v_mov_b32_e32 v93, 1.0
	v_mov_b32_e32 v94, 1.0
	v_mov_b32_e32 v95, 1.0
	s_abs_i32 s9, s5
	s_mul_hi_u32 s20, s9, s33
	s_mul_i32 s21, s20, s4
	s_sub_i32 s9, s9, s21
	s_ashr_i32 s8, s5, 31
	s_add_i32 s21, s20, 1
	s_sub_i32 s22, s9, s4
	s_cmp_ge_u32 s9, s4
	s_cselect_b32 s20, s21, s20
	s_cselect_b32 s9, s22, s9
	s_add_i32 s21, s20, 1
	s_cmp_ge_u32 s9, s4
	s_cselect_b32 s9, s21, s20
	s_xor_b32 s9, s9, s8
	s_sub_i32 s20, s9, s8
	s_lshl_b32 s21, s20, 6
	s_cmp_lt_i32 s44, 1
	v_or_b32_e32 v4, s21, v6
	s_cbranch_scc1 .LBB0_712
	s_cmp_lg_u32 s44, 1
	s_mov_b64 s[8:9], -1
	s_cbranch_scc0 .LBB0_709
	v_add_u32_e32 v2, 0xffffff20, v4
	v_cmp_lt_i32_e32 vcc, s96, v4
	s_mov_b64 s[8:9], 0
	s_nop 0
	v_cndmask_b32_e32 v2, -1, v2, vcc
	v_cmp_gt_i32_e32 vcc, s95, v4
	s_nop 1
	v_cndmask_b32_e32 v2, v2, v4, vcc

; DI int convert_weight(LAS unsigned char* lds, const WDesc d, int G, int bid, int goff) {
;     ...
;         for (int j = 0; j < 4; ++j) {
;             const int t = t0 + j, tc = t / nkt, tk = t % nkt;
;             const int cc = tid & 63, c = tc * 64 + cc;
;             int col; const float* src = d.s0;
;             if (d.map == 0) col = c;
;             else if (d.map == 1) { col = (c >> 8) * 128 + (c & 127); if (c & 128) src = d.s1; }
;             else { col = c < 2080 ? c : (c < 2304 ? -1 : c - 224); }
; #pragma unroll
;             for (int i = 0; i < 8; ++i) {
;                 const int kk = (tid >> 6) + 8 * i, k = tk * 64 + kk;
;                 float x = 0.f;
;                 if (t < ntile && col >= 0 && k < d.ksrc) { x = src[(size_t)k * d.ldsrc + col]; if (d.gain) x *= d.gain[k]; }
;                 v[j][i] = x;
.LBB0_713:
	s_mul_i32 s8, s45, s20
	s_add_i32 s20, s8, s46
	v_add_u32_e32 v2, s20, v7
	v_cmp_lt_i32_e64 s[8:9], -1, v4
	v_mov_b32_e32 v5, v1
	v_cmp_gt_i32_e32 vcc, s43, v2
	v_lshl_add_u64 v[4:5], v[4:5], 2, s[22:23]
	s_and_b64 s[24:25], s[8:9], vcc
	v_mov_b32_e32 v11, 0
	v_mov_b32_e32 v12, 0
	s_and_saveexec_b64 s[22:23], s[24:25]
	s_cbranch_execz .LBB0_716
	v_ashrrev_i32_e32 v3, 31, v2
	v_mul_lo_u32 v14, s17, v2
	v_mul_lo_u32 v15, s16, v3
	v_mad_u64_u32 v[12:13], s[24:25], s16, v2, 0
	v_add3_u32 v13, v13, v15, v14
	v_lshl_add_u64 v[12:13], v[12:13], 2, v[4:5]
	global_load_dword v12, v[12:13], off
	s_andn2_b64 vcc, exec, s[18:19]
	s_cbranch_vccnz .LBB0_716
	v_lshl_add_u64 v[14:15], v[2:3], 2, s[12:13]
	global_load_dword v64, v[14:15], off
.LBB0_716:
	s_or_b64 exec, exec, s[22:23]
	v_add_u32_e32 v3, 8, v2
	v_cmp_gt_i32_e32 vcc, s43, v3
	s_and_b64 s[24:25], s[8:9], vcc
	s_and_saveexec_b64 s[22:23], s[24:25]
	s_cbranch_execz .LBB0_719
	v_ashrrev_i32_e32 v11, 31, v3
	v_mul_lo_u32 v13, s17, v3
	v_mul_lo_u32 v11, s16, v11
	v_mad_u64_u32 v[14:15], s[24:25], s16, v3, 0
	v_add3_u32 v15, v15, v11, v13
	v_lshl_add_u64 v[14:15], v[14:15], 2, v[4:5]
	global_load_dword v11, v[14:15], off
	s_andn2_b64 vcc, exec, s[18:19]
	s_cbranch_vccnz .LBB0_719
	v_ashrrev_i32_e32 v3, 31, v2
	v_lshl_add_u64 v[14:15], v[2:3], 2, s[12:13]
	global_load_dword v65, v[14:15], off offset:32
.LBB0_719:
	s_or_b64 exec, exec, s[22:23]
	v_add_u32_e32 v3, 16, v2
	v_cmp_gt_i32_e32 vcc, s43, v3
	s_and_b64 s[24:25], s[8:9], vcc
	v_mov_b32_e32 v13, 0
	v_mov_b32_e32 v14, 0
	s_and_saveexec_b64 s[22:23], s[24:25]
	s_cbranch_execz .LBB0_722
	v_ashrrev_i32_e32 v14, 31, v3
	s_waitcnt lgkmcnt(0)
	v_mul_lo_u32 v16, s17, v3
	v_mul_lo_u32 v17, s16, v14
	v_mad_u64_u32 v[14:15], s[24:25], s16, v3, 0
	v_add3_u32 v15, v15, v17, v16
	v_lshl_add_u64 v[14:15], v[14:15], 2, v[4:5]
	global_load_dword v14, v[14:15], off
	s_andn2_b64 vcc, exec, s[18:19]
	s_cbranch_vccnz .LBB0_722
	v_ashrrev_i32_e32 v3, 31, v2
	v_lshl_add_u64 v[16:17], v[2:3], 2, s[12:13]
	global_load_dword v66, v[16:17], off offset:64
.LBB0_722:
	s_or_b64 exec, exec, s[22:23]
	v_add_u32_e32 v3, 24, v2
	v_cmp_gt_i32_e32 vcc, s43, v3
	s_and_b64 s[24:25], s[8:9], vcc
	s_and_saveexec_b64 s[22:23], s[24:25]
	s_cbranch_execz .LBB0_725
	v_ashrrev_i32_e32 v13, 31, v3
	v_mul_lo_u32 v15, s17, v3
	v_mul_lo_u32 v13, s16, v13
	s_waitcnt lgkmcnt(0)
	v_mad_u64_u32 v[16:17], s[24:25], s16, v3, 0
	v_add3_u32 v17, v17, v13, v15
	v_lshl_add_u64 v[16:17], v[16:17], 2, v[4:5]
	global_load_dword v13, v[16:17], off
	s_andn2_b64 vcc, exec, s[18:19]
	s_cbranch_vccnz .LBB0_725
	v_ashrrev_i32_e32 v3, 31, v2
	v_lshl_add_u64 v[16:17], v[2:3], 2, s[12:13]
	global_load_dword v67, v[16:17], off offset:96
.LBB0_725:
	s_or_b64 exec, exec, s[22:23]
	v_add_u32_e32 v3, 32, v2
	v_cmp_gt_i32_e32 vcc, s43, v3
	s_and_b64 s[24:25], s[8:9], vcc
	v_mov_b32_e32 v15, 0
	s_waitcnt lgkmcnt(0)
	v_mov_b32_e32 v16, 0
	s_and_saveexec_b64 s[22:23], s[24:25]
	s_cbranch_execz .LBB0_728
	v_ashrrev_i32_e32 v16, 31, v3
	v_mul_lo_u32 v18, s17, v3
	v_mul_lo_u32 v19, s16, v16
	v_mad_u64_u32 v[16:17], s[24:25], s16, v3, 0
	v_add3_u32 v17, v17, v19, v18
	v_lshl_add_u64 v[16:17], v[16:17], 2, v[4:5]
	global_load_dword v16, v[16:17], off
	s_andn2_b64 vcc, exec, s[18:19]
	s_cbranch_vccnz .LBB0_728
	v_ashrrev_i32_e32 v3, 31, v2
	v_lshl_add_u64 v[18:19], v[2:3], 2, s[12:13]
	global_load_dword v68, v[18:19], off offset:128
.LBB0_728:
	s_or_b64 exec, exec, s[22:23]
	v_add_u32_e32 v3, 40, v2
	v_cmp_gt_i32_e32 vcc, s43, v3
	s_and_b64 s[24:25], s[8:9], vcc
	s_and_saveexec_b64 s[22:23], s[24:25]
	s_cbranch_execz .LBB0_731
	v_ashrrev_i32_e32 v15, 31, v3
	v_mul_lo_u32 v17, s17, v3
	v_mul_lo_u32 v15, s16, v15
	v_mad_u64_u32 v[18:19], s[24:25], s16, v3, 0
	v_add3_u32 v19, v19, v15, v17
	v_lshl_add_u64 v[18:19], v[18:19], 2, v[4:5]
	global_load_dword v15, v[18:19], off
	s_andn2_b64 vcc, exec, s[18:19]
	s_cbranch_vccnz .LBB0_731
	v_ashrrev_i32_e32 v3, 31, v2
	v_lshl_add_u64 v[18:19], v[2:3], 2, s[12:13]
	global_load_dword v69, v[18:19], off offset:160
.LBB0_731:
	s_or_b64 exec, exec, s[22:23]
	v_add_u32_e32 v3, 48, v2
	v_cmp_gt_i32_e32 vcc, s43, v3
	s_and_b64 s[24:25], s[8:9], vcc
	v_mov_b32_e32 v17, 0
	v_mov_b32_e32 v18, 0
	s_and_saveexec_b64 s[22:23], s[24:25]
	s_cbranch_execz .LBB0_734
	v_ashrrev_i32_e32 v18, 31, v3
	v_mul_lo_u32 v20, s17, v3
	v_mul_lo_u32 v21, s16, v18
	v_mad_u64_u32 v[18:19], s[24:25], s16, v3, 0
	v_add3_u32 v19, v19, v21, v20
	v_lshl_add_u64 v[18:19], v[18:19], 2, v[4:5]
	global_load_dword v18, v[18:19], off
	s_andn2_b64 vcc, exec, s[18:19]
	s_cbranch_vccnz .LBB0_734
	v_ashrrev_i32_e32 v3, 31, v2
	v_lshl_add_u64 v[20:21], v[2:3], 2, s[12:13]
	global_load_dword v70, v[20:21], off offset:192
.LBB0_734:
	s_or_b64 exec, exec, s[22:23]
	v_add_u32_e32 v3, 56, v2
	v_cmp_gt_i32_e32 vcc, s43, v3
	s_and_b64 s[22:23], s[8:9], vcc
	s_and_saveexec_b64 s[8:9], s[22:23]
	s_cbranch_execz .LBB0_737
	v_ashrrev_i32_e32 v17, 31, v3
	v_mul_lo_u32 v19, s17, v3
	v_mul_lo_u32 v17, s16, v17
	v_mad_u64_u32 v[20:21], s[22:23], s16, v3, 0
	v_add3_u32 v21, v21, v17, v19
	v_lshl_add_u64 v[4:5], v[20:21], 2, v[4:5]
	global_load_dword v17, v[4:5], off
	s_andn2_b64 vcc, exec, s[18:19]
	s_cbranch_vccnz .LBB0_737
	v_ashrrev_i32_e32 v3, 31, v2
	v_lshl_add_u64 v[2:3], v[2:3], 2, s[12:13]
	global_load_dword v71, v[2:3], off offset:224

; DI int convert_weight(LAS unsigned char* lds, const WDesc d, int G, int bid, int goff) {
;     ...
;         for (int j = 0; j < 4; ++j) {
;             const int t = t0 + j, tc = t / nkt, tk = t % nkt;
;             const int cc = tid & 63, c = tc * 64 + cc;
;             int col; const float* src = d.s0;
;             if (d.map == 0) col = c;
;             else if (d.map == 1) { col = (c >> 8) * 128 + (c & 127); if (c & 128) src = d.s1; }
;             else { col = c < 2080 ? c : (c < 2304 ? -1 : c - 224); }
; #pragma unroll
;             for (int i = 0; i < 8; ++i) {
;                 const int kk = (tid >> 6) + 8 * i, k = tk * 64 + kk;
;                 float x = 0.f;
;                 if (t < ntile && col >= 0 && k < d.ksrc) { x = src[(size_t)k * d.ldsrc + col]; if (d.gain) x *= d.gain[k]; }
;                 v[j][i] = x;
.LBB0_744:
	s_mul_i32 s23, s23, s4
	s_sub_i32 s8, s22, s23
	s_lshl_b32 s8, s8, 6
	s_cmp_lt_i32 s22, s0
	v_add_u32_e32 v2, s8, v7
	s_cselect_b64 s[22:23], -1, 0
	v_cmp_lt_i32_e32 vcc, -1, v4
	s_and_b64 s[24:25], s[22:23], vcc
	v_mov_b32_e32 v5, v1
	v_cmp_gt_i32_e32 vcc, s43, v2
	v_lshl_add_u64 v[4:5], v[4:5], 2, s[26:27]
	s_and_b64 s[28:29], s[24:25], vcc
	v_mov_b32_e32 v19, 0
	v_mov_b32_e32 v20, 0
	s_and_saveexec_b64 s[26:27], s[28:29]
	s_cbranch_execz .LBB0_747
	v_ashrrev_i32_e32 v3, 31, v2
	v_mul_lo_u32 v22, s17, v2
	v_mul_lo_u32 v23, s16, v3
	v_mad_u64_u32 v[20:21], s[28:29], s16, v2, 0
	v_add3_u32 v21, v21, v23, v22
	v_lshl_add_u64 v[20:21], v[20:21], 2, v[4:5]
	global_load_dword v20, v[20:21], off
	s_andn2_b64 vcc, exec, s[18:19]
	s_cbranch_vccnz .LBB0_747
	v_lshl_add_u64 v[22:23], v[2:3], 2, s[12:13]
	global_load_dword v72, v[22:23], off
.LBB0_747:
	s_or_b64 exec, exec, s[26:27]
	v_add_u32_e32 v3, 8, v2
	v_cmp_gt_i32_e32 vcc, s43, v3
	s_and_b64 s[28:29], s[24:25], vcc
	s_and_saveexec_b64 s[26:27], s[28:29]
	s_cbranch_execz .LBB0_750
	v_ashrrev_i32_e32 v19, 31, v3
	v_mul_lo_u32 v21, s17, v3
	v_mul_lo_u32 v19, s16, v19
	v_mad_u64_u32 v[22:23], s[28:29], s16, v3, 0
	v_add3_u32 v23, v23, v19, v21
	v_lshl_add_u64 v[22:23], v[22:23], 2, v[4:5]
	global_load_dword v19, v[22:23], off
	s_andn2_b64 vcc, exec, s[18:19]
	s_cbranch_vccnz .LBB0_750
	v_ashrrev_i32_e32 v3, 31, v2
	v_lshl_add_u64 v[22:23], v[2:3], 2, s[12:13]
	global_load_dword v73, v[22:23], off offset:32
.LBB0_750:
	s_or_b64 exec, exec, s[26:27]
	v_add_u32_e32 v3, 16, v2
	v_cmp_gt_i32_e32 vcc, s43, v3
	s_and_b64 s[28:29], s[24:25], vcc
	v_mov_b32_e32 v21, 0
	v_mov_b32_e32 v22, 0
	s_and_saveexec_b64 s[26:27], s[28:29]
	s_cbranch_execz .LBB0_753
	v_ashrrev_i32_e32 v22, 31, v3
	v_mul_lo_u32 v24, s17, v3
	v_mul_lo_u32 v25, s16, v22
	v_mad_u64_u32 v[22:23], s[28:29], s16, v3, 0
	v_add3_u32 v23, v23, v25, v24
	v_lshl_add_u64 v[22:23], v[22:23], 2, v[4:5]
	global_load_dword v22, v[22:23], off
	s_andn2_b64 vcc, exec, s[18:19]
	s_cbranch_vccnz .LBB0_753
	v_ashrrev_i32_e32 v3, 31, v2
	v_lshl_add_u64 v[24:25], v[2:3], 2, s[12:13]
	global_load_dword v74, v[24:25], off offset:64
.LBB0_753:
	s_or_b64 exec, exec, s[26:27]
	v_add_u32_e32 v3, 24, v2
	v_cmp_gt_i32_e32 vcc, s43, v3
	s_and_b64 s[28:29], s[24:25], vcc
	s_and_saveexec_b64 s[26:27], s[28:29]
	s_cbranch_execz .LBB0_756
	v_ashrrev_i32_e32 v21, 31, v3
	v_mul_lo_u32 v23, s17, v3
	v_mul_lo_u32 v21, s16, v21
	v_mad_u64_u32 v[24:25], s[28:29], s16, v3, 0
	v_add3_u32 v25, v25, v21, v23
	v_lshl_add_u64 v[24:25], v[24:25], 2, v[4:5]
	global_load_dword v21, v[24:25], off
	s_andn2_b64 vcc, exec, s[18:19]
	s_cbranch_vccnz .LBB0_756
	v_ashrrev_i32_e32 v3, 31, v2
	v_lshl_add_u64 v[24:25], v[2:3], 2, s[12:13]
	global_load_dword v75, v[24:25], off offset:96
.LBB0_756:
	s_or_b64 exec, exec, s[26:27]
	v_add_u32_e32 v3, 32, v2
	v_cmp_gt_i32_e32 vcc, s43, v3
	s_and_b64 s[28:29], s[24:25], vcc
	v_mov_b32_e32 v23, 0
	v_mov_b32_e32 v24, 0
	s_and_saveexec_b64 s[26:27], s[28:29]
	s_cbranch_execz .LBB0_759
	v_ashrrev_i32_e32 v24, 31, v3
	v_mul_lo_u32 v26, s17, v3
	v_mul_lo_u32 v27, s16, v24
	v_mad_u64_u32 v[24:25], s[28:29], s16, v3, 0
	v_add3_u32 v25, v25, v27, v26
	v_lshl_add_u64 v[24:25], v[24:25], 2, v[4:5]
	global_load_dword v24, v[24:25], off
	s_andn2_b64 vcc, exec, s[18:19]
	s_cbranch_vccnz .LBB0_759
	v_ashrrev_i32_e32 v3, 31, v2
	v_lshl_add_u64 v[26:27], v[2:3], 2, s[12:13]
	global_load_dword v76, v[26:27], off offset:128
.LBB0_759:
	s_or_b64 exec, exec, s[26:27]
	v_add_u32_e32 v3, 40, v2
	v_cmp_gt_i32_e32 vcc, s43, v3
	s_and_b64 s[28:29], s[24:25], vcc
	s_and_saveexec_b64 s[26:27], s[28:29]
	s_cbranch_execz .LBB0_762
	v_ashrrev_i32_e32 v23, 31, v3
	v_mul_lo_u32 v25, s17, v3
	v_mul_lo_u32 v23, s16, v23
	v_mad_u64_u32 v[26:27], s[28:29], s16, v3, 0
	v_add3_u32 v27, v27, v23, v25
	v_lshl_add_u64 v[26:27], v[26:27], 2, v[4:5]
	global_load_dword v23, v[26:27], off
	s_andn2_b64 vcc, exec, s[18:19]
	s_cbranch_vccnz .LBB0_762
	v_ashrrev_i32_e32 v3, 31, v2
	v_lshl_add_u64 v[26:27], v[2:3], 2, s[12:13]
	global_load_dword v77, v[26:27], off offset:160
.LBB0_762:
	s_or_b64 exec, exec, s[26:27]
	v_add_u32_e32 v3, 48, v2
	v_cmp_gt_i32_e32 vcc, s43, v3
	s_and_b64 s[28:29], s[24:25], vcc
	v_mov_b32_e32 v25, 0
	v_mov_b32_e32 v26, 0
	s_and_saveexec_b64 s[26:27], s[28:29]
	s_cbranch_execz .LBB0_765
	v_ashrrev_i32_e32 v26, 31, v3
	v_mul_lo_u32 v28, s17, v3
	v_mul_lo_u32 v29, s16, v26
	v_mad_u64_u32 v[26:27], s[28:29], s16, v3, 0
	v_add3_u32 v27, v27, v29, v28
	v_lshl_add_u64 v[26:27], v[26:27], 2, v[4:5]
	global_load_dword v26, v[26:27], off
	s_andn2_b64 vcc, exec, s[18:19]
	s_cbranch_vccnz .LBB0_765
	v_ashrrev_i32_e32 v3, 31, v2
	v_lshl_add_u64 v[28:29], v[2:3], 2, s[12:13]
	global_load_dword v78, v[28:29], off offset:192
.LBB0_765:
	s_or_b64 exec, exec, s[26:27]
	v_add_u32_e32 v3, 56, v2
	v_cmp_gt_i32_e32 vcc, s43, v3
	s_and_b64 s[26:27], s[24:25], vcc
	s_and_saveexec_b64 s[24:25], s[26:27]
	s_cbranch_execz .LBB0_768
	v_ashrrev_i32_e32 v25, 31, v3
	v_mul_lo_u32 v27, s17, v3
	v_mul_lo_u32 v25, s16, v25
	v_mad_u64_u32 v[28:29], s[26:27], s16, v3, 0
	v_add3_u32 v29, v29, v25, v27
	v_lshl_add_u64 v[4:5], v[28:29], 2, v[4:5]
	global_load_dword v25, v[4:5], off
	s_andn2_b64 vcc, exec, s[18:19]
	s_cbranch_vccnz .LBB0_768
	v_ashrrev_i32_e32 v3, 31, v2
	v_lshl_add_u64 v[2:3], v[2:3], 2, s[12:13]
	global_load_dword v79, v[2:3], off offset:224

; DI int convert_weight(LAS unsigned char* lds, const WDesc d, int G, int bid, int goff) {
;     ...
;         for (int j = 0; j < 4; ++j) {
;             const int t = t0 + j, tc = t / nkt, tk = t % nkt;
;             const int cc = tid & 63, c = tc * 64 + cc;
;             int col; const float* src = d.s0;
;             if (d.map == 0) col = c;
;             else if (d.map == 1) { col = (c >> 8) * 128 + (c & 127); if (c & 128) src = d.s1; }
;             else { col = c < 2080 ? c : (c < 2304 ? -1 : c - 224); }
; #pragma unroll
;             for (int i = 0; i < 8; ++i) {
;                 const int kk = (tid >> 6) + 8 * i, k = tk * 64 + kk;
;                 float x = 0.f;
;                 if (t < ntile && col >= 0 && k < d.ksrc) { x = src[(size_t)k * d.ldsrc + col]; if (d.gain) x *= d.gain[k]; }
;                 v[j][i] = x;
.LBB0_775:
	s_mul_i32 s26, s26, s4
	s_sub_i32 s24, s9, s26
	s_lshl_b32 s24, s24, 6
	s_cmp_lt_i32 s9, s0
	v_add_u32_e32 v2, s24, v7
	s_cselect_b64 s[26:27], -1, 0
	v_cmp_lt_i32_e32 vcc, -1, v4
	s_and_b64 s[28:29], s[26:27], vcc
	v_mov_b32_e32 v5, v1
	v_cmp_gt_i32_e32 vcc, s43, v2
	v_lshl_add_u64 v[4:5], v[4:5], 2, s[30:31]
	s_and_b64 s[34:35], s[28:29], vcc
	v_mov_b32_e32 v27, 0
	v_mov_b32_e32 v28, 0
	s_and_saveexec_b64 s[30:31], s[34:35]
	s_cbranch_execz .LBB0_778
	v_ashrrev_i32_e32 v3, 31, v2
	v_mul_lo_u32 v30, s17, v2
	v_mul_lo_u32 v31, s16, v3
	v_mad_u64_u32 v[28:29], s[34:35], s16, v2, 0
	v_add3_u32 v29, v29, v31, v30
	v_lshl_add_u64 v[28:29], v[28:29], 2, v[4:5]
	global_load_dword v28, v[28:29], off
	s_andn2_b64 vcc, exec, s[18:19]
	s_cbranch_vccnz .LBB0_778
	v_lshl_add_u64 v[30:31], v[2:3], 2, s[12:13]
	global_load_dword v80, v[30:31], off
.LBB0_778:
	s_or_b64 exec, exec, s[30:31]
	v_add_u32_e32 v3, 8, v2
	v_cmp_gt_i32_e32 vcc, s43, v3
	s_and_b64 s[34:35], s[28:29], vcc
	s_and_saveexec_b64 s[30:31], s[34:35]
	s_cbranch_execz .LBB0_781
	v_ashrrev_i32_e32 v27, 31, v3
	v_mul_lo_u32 v29, s17, v3
	v_mul_lo_u32 v27, s16, v27
	v_mad_u64_u32 v[30:31], s[34:35], s16, v3, 0
	v_add3_u32 v31, v31, v27, v29
	v_lshl_add_u64 v[30:31], v[30:31], 2, v[4:5]
	global_load_dword v27, v[30:31], off
	s_andn2_b64 vcc, exec, s[18:19]
	s_cbranch_vccnz .LBB0_781
	v_ashrrev_i32_e32 v3, 31, v2
	v_lshl_add_u64 v[30:31], v[2:3], 2, s[12:13]
	global_load_dword v81, v[30:31], off offset:32
.LBB0_781:
	s_or_b64 exec, exec, s[30:31]
	v_add_u32_e32 v3, 16, v2
	v_cmp_gt_i32_e32 vcc, s43, v3
	s_and_b64 s[34:35], s[28:29], vcc
	v_mov_b32_e32 v29, 0
	v_mov_b32_e32 v30, 0
	s_and_saveexec_b64 s[30:31], s[34:35]
	s_cbranch_execz .LBB0_784
	v_ashrrev_i32_e32 v30, 31, v3
	v_mul_lo_u32 v32, s17, v3
	v_mul_lo_u32 v33, s16, v30
	v_mad_u64_u32 v[30:31], s[34:35], s16, v3, 0
	v_add3_u32 v31, v31, v33, v32
	v_lshl_add_u64 v[30:31], v[30:31], 2, v[4:5]
	global_load_dword v30, v[30:31], off
	s_andn2_b64 vcc, exec, s[18:19]
	s_cbranch_vccnz .LBB0_784
	v_ashrrev_i32_e32 v3, 31, v2
	v_lshl_add_u64 v[32:33], v[2:3], 2, s[12:13]
	global_load_dword v82, v[32:33], off offset:64
.LBB0_784:
	s_or_b64 exec, exec, s[30:31]
	v_add_u32_e32 v3, 24, v2
	v_cmp_gt_i32_e32 vcc, s43, v3
	s_and_b64 s[34:35], s[28:29], vcc
	s_and_saveexec_b64 s[30:31], s[34:35]
	s_cbranch_execz .LBB0_787
	v_ashrrev_i32_e32 v29, 31, v3
	v_mul_lo_u32 v31, s17, v3
	v_mul_lo_u32 v29, s16, v29
	v_mad_u64_u32 v[32:33], s[34:35], s16, v3, 0
	v_add3_u32 v33, v33, v29, v31
	v_lshl_add_u64 v[32:33], v[32:33], 2, v[4:5]
	global_load_dword v29, v[32:33], off
	s_andn2_b64 vcc, exec, s[18:19]
	s_cbranch_vccnz .LBB0_787
	v_ashrrev_i32_e32 v3, 31, v2
	v_lshl_add_u64 v[32:33], v[2:3], 2, s[12:13]
	global_load_dword v83, v[32:33], off offset:96
.LBB0_787:
	s_or_b64 exec, exec, s[30:31]
	v_add_u32_e32 v3, 32, v2
	v_cmp_gt_i32_e32 vcc, s43, v3
	s_and_b64 s[34:35], s[28:29], vcc
	v_mov_b32_e32 v31, 0
	v_mov_b32_e32 v32, 0
	s_and_saveexec_b64 s[30:31], s[34:35]
	s_cbranch_execz .LBB0_790
	v_ashrrev_i32_e32 v32, 31, v3
	v_mul_lo_u32 v34, s17, v3
	v_mul_lo_u32 v35, s16, v32
	v_mad_u64_u32 v[32:33], s[34:35], s16, v3, 0
	v_add3_u32 v33, v33, v35, v34
	v_lshl_add_u64 v[32:33], v[32:33], 2, v[4:5]
	global_load_dword v32, v[32:33], off
	s_andn2_b64 vcc, exec, s[18:19]
	s_cbranch_vccnz .LBB0_790
	v_ashrrev_i32_e32 v3, 31, v2
	v_lshl_add_u64 v[34:35], v[2:3], 2, s[12:13]
	global_load_dword v84, v[34:35], off offset:128
.LBB0_790:
	s_or_b64 exec, exec, s[30:31]
	v_add_u32_e32 v3, 40, v2
	v_cmp_gt_i32_e32 vcc, s43, v3
	s_and_b64 s[34:35], s[28:29], vcc
	s_and_saveexec_b64 s[30:31], s[34:35]
	s_cbranch_execz .LBB0_793
	v_ashrrev_i32_e32 v31, 31, v3
	v_mul_lo_u32 v33, s17, v3
	v_mul_lo_u32 v31, s16, v31
	v_mad_u64_u32 v[34:35], s[34:35], s16, v3, 0
	v_add3_u32 v35, v35, v31, v33
	v_lshl_add_u64 v[34:35], v[34:35], 2, v[4:5]
	global_load_dword v31, v[34:35], off
	s_andn2_b64 vcc, exec, s[18:19]
	s_cbranch_vccnz .LBB0_793
	v_ashrrev_i32_e32 v3, 31, v2
	v_lshl_add_u64 v[34:35], v[2:3], 2, s[12:13]
	global_load_dword v85, v[34:35], off offset:160
.LBB0_793:
	s_or_b64 exec, exec, s[30:31]
	v_add_u32_e32 v3, 48, v2
	v_cmp_gt_i32_e32 vcc, s43, v3
	s_and_b64 s[34:35], s[28:29], vcc
	v_mov_b32_e32 v33, 0
	v_mov_b32_e32 v34, 0
	s_and_saveexec_b64 s[30:31], s[34:35]
	s_cbranch_execz .LBB0_796
	v_ashrrev_i32_e32 v34, 31, v3
	v_mul_lo_u32 v36, s17, v3
	v_mul_lo_u32 v37, s16, v34
	v_mad_u64_u32 v[34:35], s[34:35], s16, v3, 0
	v_add3_u32 v35, v35, v37, v36
	v_lshl_add_u64 v[34:35], v[34:35], 2, v[4:5]
	global_load_dword v34, v[34:35], off
	s_andn2_b64 vcc, exec, s[18:19]
	s_cbranch_vccnz .LBB0_796
	v_ashrrev_i32_e32 v3, 31, v2
	v_lshl_add_u64 v[36:37], v[2:3], 2, s[12:13]
	global_load_dword v86, v[36:37], off offset:192
.LBB0_796:
	s_or_b64 exec, exec, s[30:31]
	v_add_u32_e32 v3, 56, v2
	v_cmp_gt_i32_e32 vcc, s43, v3
	s_and_b64 s[30:31], s[28:29], vcc
	s_and_saveexec_b64 s[28:29], s[30:31]
	s_cbranch_execz .LBB0_799
	v_ashrrev_i32_e32 v33, 31, v3
	v_mul_lo_u32 v35, s17, v3
	v_mul_lo_u32 v33, s16, v33
	v_mad_u64_u32 v[36:37], s[30:31], s16, v3, 0
	v_add3_u32 v37, v37, v33, v35
	v_lshl_add_u64 v[4:5], v[36:37], 2, v[4:5]
	global_load_dword v33, v[4:5], off
	s_andn2_b64 vcc, exec, s[18:19]
	s_cbranch_vccnz .LBB0_799
	v_ashrrev_i32_e32 v3, 31, v2
	v_lshl_add_u64 v[2:3], v[2:3], 2, s[12:13]
	global_load_dword v87, v[2:3], off offset:224

; DI int convert_weight(LAS unsigned char* lds, const WDesc d, int G, int bid, int goff) {
;     ...
;         for (int j = 0; j < 4; ++j) {
;             const int t = t0 + j, tc = t / nkt, tk = t % nkt;
;             const int cc = tid & 63, c = tc * 64 + cc;
;             int col; const float* src = d.s0;
;             if (d.map == 0) col = c;
;             else if (d.map == 1) { col = (c >> 8) * 128 + (c & 127); if (c & 128) src = d.s1; }
;             else { col = c < 2080 ? c : (c < 2304 ? -1 : c - 224); }
; #pragma unroll
;             for (int i = 0; i < 8; ++i) {
;                 const int kk = (tid >> 6) + 8 * i, k = tk * 64 + kk;
;                 float x = 0.f;
;                 if (t < ntile && col >= 0 && k < d.ksrc) { x = src[(size_t)k * d.ldsrc + col]; if (d.gain) x *= d.gain[k]; }
;                 v[j][i] = x;
.LBB0_806:
	s_mul_i32 s25, s25, s4
	s_sub_i32 s25, s9, s25
	s_lshl_b32 s28, s25, 6
	s_cmp_lt_i32 s9, s0
	v_add_u32_e32 v2, s28, v7
	s_cselect_b64 s[30:31], -1, 0
	v_cmp_lt_i32_e32 vcc, -1, v4
	s_and_b64 s[34:35], s[30:31], vcc
	v_mov_b32_e32 v5, v1
	v_cmp_gt_i32_e32 vcc, s43, v2
	v_lshl_add_u64 v[4:5], v[4:5], 2, s[36:37]
	s_and_b64 s[52:53], s[34:35], vcc
	v_mov_b32_e32 v35, 0
	v_mov_b32_e32 v36, 0
	s_and_saveexec_b64 s[36:37], s[52:53]
	s_cbranch_execz .LBB0_809
	v_ashrrev_i32_e32 v3, 31, v2
	v_mul_lo_u32 v38, s17, v2
	v_mul_lo_u32 v39, s16, v3
	v_mad_u64_u32 v[36:37], s[52:53], s16, v2, 0
	v_add3_u32 v37, v37, v39, v38
	v_lshl_add_u64 v[36:37], v[36:37], 2, v[4:5]
	global_load_dword v36, v[36:37], off
	s_andn2_b64 vcc, exec, s[18:19]
	s_cbranch_vccnz .LBB0_809
	v_lshl_add_u64 v[38:39], v[2:3], 2, s[12:13]
	global_load_dword v88, v[38:39], off
.LBB0_809:
	s_or_b64 exec, exec, s[36:37]
	v_add_u32_e32 v3, 8, v2
	v_cmp_gt_i32_e32 vcc, s43, v3
	s_and_b64 s[52:53], s[34:35], vcc
	s_and_saveexec_b64 s[36:37], s[52:53]
	s_cbranch_execz .LBB0_812
	v_ashrrev_i32_e32 v35, 31, v3
	v_mul_lo_u32 v37, s17, v3
	v_mul_lo_u32 v35, s16, v35
	v_mad_u64_u32 v[38:39], s[52:53], s16, v3, 0
	v_add3_u32 v39, v39, v35, v37
	v_lshl_add_u64 v[38:39], v[38:39], 2, v[4:5]
	global_load_dword v35, v[38:39], off
	s_andn2_b64 vcc, exec, s[18:19]
	s_cbranch_vccnz .LBB0_812
	v_ashrrev_i32_e32 v3, 31, v2
	v_lshl_add_u64 v[38:39], v[2:3], 2, s[12:13]
	global_load_dword v89, v[38:39], off offset:32
.LBB0_812:
	s_or_b64 exec, exec, s[36:37]
	v_add_u32_e32 v3, 16, v2
	v_cmp_gt_i32_e32 vcc, s43, v3
	s_and_b64 s[52:53], s[34:35], vcc
	v_mov_b32_e32 v37, 0
	v_mov_b32_e32 v38, 0
	s_and_saveexec_b64 s[36:37], s[52:53]
	s_cbranch_execz .LBB0_815
	v_ashrrev_i32_e32 v38, 31, v3
	v_mul_lo_u32 v40, s17, v3
	v_mul_lo_u32 v41, s16, v38
	v_mad_u64_u32 v[38:39], s[52:53], s16, v3, 0
	v_add3_u32 v39, v39, v41, v40
	v_lshl_add_u64 v[38:39], v[38:39], 2, v[4:5]
	global_load_dword v38, v[38:39], off
	s_andn2_b64 vcc, exec, s[18:19]
	s_cbranch_vccnz .LBB0_815
	v_ashrrev_i32_e32 v3, 31, v2
	v_lshl_add_u64 v[40:41], v[2:3], 2, s[12:13]
	global_load_dword v90, v[40:41], off offset:64
.LBB0_815:
	s_or_b64 exec, exec, s[36:37]
	v_add_u32_e32 v3, 24, v2
	v_cmp_gt_i32_e32 vcc, s43, v3
	s_and_b64 s[52:53], s[34:35], vcc
	s_and_saveexec_b64 s[36:37], s[52:53]
	s_cbranch_execz .LBB0_818
	v_ashrrev_i32_e32 v37, 31, v3
	v_mul_lo_u32 v39, s17, v3
	v_mul_lo_u32 v37, s16, v37
	v_mad_u64_u32 v[40:41], s[52:53], s16, v3, 0
	v_add3_u32 v41, v41, v37, v39
	v_lshl_add_u64 v[40:41], v[40:41], 2, v[4:5]
	global_load_dword v37, v[40:41], off
	s_andn2_b64 vcc, exec, s[18:19]
	s_cbranch_vccnz .LBB0_818
	v_ashrrev_i32_e32 v3, 31, v2
	v_lshl_add_u64 v[40:41], v[2:3], 2, s[12:13]
	global_load_dword v91, v[40:41], off offset:96
.LBB0_818:
	s_or_b64 exec, exec, s[36:37]
	v_add_u32_e32 v3, 32, v2
	v_cmp_gt_i32_e32 vcc, s43, v3
	s_and_b64 s[52:53], s[34:35], vcc
	v_mov_b32_e32 v39, 0
	v_mov_b32_e32 v40, 0
	s_and_saveexec_b64 s[36:37], s[52:53]
	s_cbranch_execz .LBB0_821
	v_ashrrev_i32_e32 v40, 31, v3
	v_mul_lo_u32 v42, s17, v3
	v_mul_lo_u32 v43, s16, v40
	v_mad_u64_u32 v[40:41], s[52:53], s16, v3, 0
	v_add3_u32 v41, v41, v43, v42
	v_lshl_add_u64 v[40:41], v[40:41], 2, v[4:5]
	global_load_dword v40, v[40:41], off
	s_andn2_b64 vcc, exec, s[18:19]
	s_cbranch_vccnz .LBB0_821
	v_ashrrev_i32_e32 v3, 31, v2
	v_lshl_add_u64 v[42:43], v[2:3], 2, s[12:13]
	global_load_dword v92, v[42:43], off offset:128
.LBB0_821:
	s_or_b64 exec, exec, s[36:37]
	v_add_u32_e32 v3, 40, v2
	v_cmp_gt_i32_e32 vcc, s43, v3
	s_and_b64 s[52:53], s[34:35], vcc
	s_and_saveexec_b64 s[36:37], s[52:53]
	s_cbranch_execz .LBB0_824
	v_ashrrev_i32_e32 v39, 31, v3
	v_mul_lo_u32 v41, s17, v3
	v_mul_lo_u32 v39, s16, v39
	v_mad_u64_u32 v[42:43], s[52:53], s16, v3, 0
	v_add3_u32 v43, v43, v39, v41
	v_lshl_add_u64 v[42:43], v[42:43], 2, v[4:5]
	global_load_dword v39, v[42:43], off
	s_andn2_b64 vcc, exec, s[18:19]
	s_cbranch_vccnz .LBB0_824
	v_ashrrev_i32_e32 v3, 31, v2
	v_lshl_add_u64 v[42:43], v[2:3], 2, s[12:13]
	global_load_dword v93, v[42:43], off offset:160
.LBB0_824:
	s_or_b64 exec, exec, s[36:37]
	v_add_u32_e32 v3, 48, v2
	v_cmp_gt_i32_e32 vcc, s43, v3
	s_and_b64 s[52:53], s[34:35], vcc
	v_mov_b32_e32 v41, 0
	v_mov_b32_e32 v42, 0
	s_and_saveexec_b64 s[36:37], s[52:53]
	s_cbranch_execz .LBB0_827
	v_ashrrev_i32_e32 v42, 31, v3
	v_mul_lo_u32 v44, s17, v3
	v_mul_lo_u32 v45, s16, v42
	v_mad_u64_u32 v[42:43], s[52:53], s16, v3, 0
	v_add3_u32 v43, v43, v45, v44
	v_lshl_add_u64 v[42:43], v[42:43], 2, v[4:5]
	global_load_dword v42, v[42:43], off
	s_andn2_b64 vcc, exec, s[18:19]
	s_cbranch_vccnz .LBB0_827
	v_ashrrev_i32_e32 v3, 31, v2
	v_lshl_add_u64 v[44:45], v[2:3], 2, s[12:13]
	global_load_dword v94, v[44:45], off offset:192
; #define LAS __attribute__((address_space(3)))
; DI unsigned pk2(float lo, float hi) { f32x2_t v = {lo, hi}; bf16x2_t b = __builtin_convertvector(v, bf16x2_t); return __builtin_bit_cast(unsigned, b); }
; DI int convert_weight(LAS unsigned char* lds, const WDesc d, int G, int bid, int goff) {
;     ...
;                 if (t < ntile && col >= 0 && k < d.ksrc) { x = src[(size_t)k * d.ldsrc + col]; if (d.gain) x *= d.gain[k]; }
;                 v[j][i] = x;
;             }
;         }
;         __syncthreads();
; #pragma unroll
;         for (int j = 0; j < 4; ++j)
; #pragma unroll
;             for (int i = 0; i < 8; ++i) tl[j * 64 * 66 + (tid & 63) * 66 + (tid >> 6) + 8 * i] = (bf16_t)(pk2(v[j][i], 0.f) & 0xffff);
;         __syncthreads();
; #pragma unroll
;         for (int j = 0; j < 4; ++j) {
;             const int t = t0 + j, tc = t / nkt, tk = t % nkt;
;             const int rr = tid >> 3, kc = tid & 7;
;             const LAS unsigned* sp = (const LAS unsigned*)(tl + j * 64 * 66 + rr * 66 + kc * 8);
;             u32x4 w; w.x = sp[0]; w.y = sp[1]; w.z = sp[2]; w.w = sp[3];
;             if (t < ntile) *(u32x4*)(d.dst + (size_t)(tc * 64 + rr) * d.kdst + tk * 64 + kc * 8) = w;
;         }
.LBB0_827:
	s_or_b64 exec, exec, s[36:37]
	v_add_u32_e32 v3, 56, v2
	v_cmp_gt_i32_e32 vcc, s43, v3
	s_and_b64 s[36:37], s[34:35], vcc
	s_and_saveexec_b64 s[34:35], s[36:37]
	s_cbranch_execz .LBB0_830
	v_ashrrev_i32_e32 v41, 31, v3
	v_mul_lo_u32 v43, s17, v3
	v_mul_lo_u32 v41, s16, v41
	v_mad_u64_u32 v[44:45], s[36:37], s16, v3, 0
	v_add3_u32 v45, v45, v41, v43
	v_lshl_add_u64 v[4:5], v[44:45], 2, v[4:5]
	global_load_dword v41, v[4:5], off
	s_andn2_b64 vcc, exec, s[18:19]
	s_cbranch_vccnz .LBB0_830
	v_ashrrev_i32_e32 v3, 31, v2
	v_lshl_add_u64 v[2:3], v[2:3], 2, s[12:13]
	global_load_dword v95, v[2:3], off offset:224
.LBB0_830:
	s_or_b64 exec, exec, s[34:35]
	s_waitcnt vmcnt(0)
	v_mul_f32_e32 v12, v12, v64
	v_mul_f32_e32 v11, v11, v65
	v_mul_f32_e32 v14, v14, v66
	v_mul_f32_e32 v13, v13, v67
	v_mul_f32_e32 v16, v16, v68
	v_mul_f32_e32 v15, v15, v69
	v_mul_f32_e32 v18, v18, v70
	v_mul_f32_e32 v17, v17, v71
	v_mul_f32_e32 v20, v20, v72
	v_mul_f32_e32 v19, v19, v73
	v_mul_f32_e32 v22, v22, v74
	v_mul_f32_e32 v21, v21, v75
	v_mul_f32_e32 v24, v24, v76
	v_mul_f32_e32 v23, v23, v77
	v_mul_f32_e32 v26, v26, v78
	v_mul_f32_e32 v25, v25, v79
	v_mul_f32_e32 v28, v28, v80
	v_mul_f32_e32 v27, v27, v81
	v_mul_f32_e32 v30, v30, v82
	v_mul_f32_e32 v29, v29, v83
	v_mul_f32_e32 v32, v32, v84
	v_mul_f32_e32 v31, v31, v85
	v_mul_f32_e32 v34, v34, v86
	v_mul_f32_e32 v33, v33, v87
	v_mul_f32_e32 v36, v36, v88
	v_mul_f32_e32 v35, v35, v89
	v_mul_f32_e32 v38, v38, v90
	v_mul_f32_e32 v37, v37, v91
	v_mul_f32_e32 v40, v40, v92
	v_mul_f32_e32 v39, v39, v93
	v_mul_f32_e32 v42, v42, v94
	v_mul_f32_e32 v41, v41, v95
	v_cvt_pk_bf16_f32 v2, v12, s0
	s_barrier
	ds_write_b16 v8, v2
	v_cvt_pk_bf16_f32 v2, v11, s0
	ds_write_b16 v8, v2 offset:16
	v_cvt_pk_bf16_f32 v2, v14, s0
	ds_write_b16 v8, v2 offset:32
	v_cvt_pk_bf16_f32 v2, v13, s0
	ds_write_b16 v8, v2 offset:48
	v_cvt_pk_bf16_f32 v2, v16, s0
	ds_write_b16 v8, v2 offset:64
	v_cvt_pk_bf16_f32 v2, v15, s0
	ds_write_b16 v8, v2 offset:80
	v_cvt_pk_bf16_f32 v2, v18, s0
	ds_write_b16 v8, v2 offset:96
	v_cvt_pk_bf16_f32 v2, v17, s0
	ds_write_b16 v8, v2 offset:112
	v_cvt_pk_bf16_f32 v2, v20, s0
	ds_write_b16 v8, v2 offset:8448
	v_cvt_pk_bf16_f32 v2, v19, s0
	ds_write_b16 v8, v2 offset:8464
	v_cvt_pk_bf16_f32 v2, v22, s0
	ds_write_b16 v8, v2 offset:8480
	v_cvt_pk_bf16_f32 v2, v21, s0
	ds_write_b16 v8, v2 offset:8496
	v_cvt_pk_bf16_f32 v2, v24, s0
	ds_write_b16 v8, v2 offset:8512
	v_cvt_pk_bf16_f32 v2, v23, s0
	ds_write_b16 v8, v2 offset:8528
	v_cvt_pk_bf16_f32 v2, v26, s0
	ds_write_b16 v8, v2 offset:8544
	v_cvt_pk_bf16_f32 v2, v25, s0
	ds_write_b16 v8, v2 offset:8560
	v_cvt_pk_bf16_f32 v2, v28, s0
	ds_write_b16 v8, v2 offset:16896
	v_cvt_pk_bf16_f32 v2, v27, s0
	ds_write_b16 v8, v2 offset:16912
	v_cvt_pk_bf16_f32 v2, v30, s0
	ds_write_b16 v8, v2 offset:16928
	v_cvt_pk_bf16_f32 v2, v29, s0
	ds_write_b16 v8, v2 offset:16944
	v_cvt_pk_bf16_f32 v2, v32, s0
	ds_write_b16 v8, v2 offset:16960
	v_cvt_pk_bf16_f32 v2, v31, s0
	ds_write_b16 v8, v2 offset:16976
	v_cvt_pk_bf16_f32 v2, v34, s0
	ds_write_b16 v8, v2 offset:16992
	v_cvt_pk_bf16_f32 v2, v33, s0
	ds_write_b16 v8, v2 offset:17008
	v_cvt_pk_bf16_f32 v2, v36, s0
	ds_write_b16 v8, v2 offset:25344
	v_cvt_pk_bf16_f32 v2, v35, s0
	ds_write_b16 v8, v2 offset:25360
	v_cvt_pk_bf16_f32 v2, v38, s0
	ds_write_b16 v8, v2 offset:25376
	v_cvt_pk_bf16_f32 v2, v37, s0
	ds_write_b16 v8, v2 offset:25392
	v_cvt_pk_bf16_f32 v2, v40, s0
	ds_write_b16 v8, v2 offset:25408
	v_cvt_pk_bf16_f32 v2, v39, s0
	v_add_u32_e32 v11, s21, v9
	ds_write_b16 v8, v2 offset:25424
	v_cvt_pk_bf16_f32 v2, v42, s0
	v_mad_u64_u32 v[12:13], s[34:35], v11, s1, 0
	ds_write_b16 v8, v2 offset:25440
	v_cvt_pk_bf16_f32 v2, v41, s0
	v_ashrrev_i32_e32 v15, 31, v11
	v_mov_b32_e32 v14, v13
	ds_write_b16 v8, v2 offset:25456
	s_waitcnt lgkmcnt(0)
	s_barrier
	ds_read2_b32 v[2:3], v10 offset1:1
	ds_read2_b32 v[4:5], v10 offset0:2 offset1:3
	v_mad_u64_u32 v[14:15], s[34:35], v15, s1, v[14:15]
	v_mov_b32_e32 v13, v14
	v_lshl_add_u64 v[12:13], v[12:13], 1, s[10:11]
	s_ashr_i32 s21, s20, 31
	v_lshl_add_u64 v[12:13], s[20:21], 1, v[12:13]
	v_lshl_add_u64 v[12:13], v[12:13], 0, v[0:1]
	s_andn2_b64 vcc, exec, s[22:23]
	s_waitcnt lgkmcnt(0)
	global_store_dwordx4 v[12:13], v[2:5], off
	s_cbranch_vccnz .LBB0_833
	v_add_u32_e32 v11, s48, v9
	v_mad_u64_u32 v[12:13], s[20:21], v11, s1, 0
	v_add_u32_e32 v2, 0x2100, v10
	v_add_u32_e32 v4, 0x2108, v10
	v_ashrrev_i32_e32 v15, 31, v11
	v_mov_b32_e32 v14, v13
	ds_read2_b32 v[2:3], v2 offset1:1
	ds_read2_b32 v[4:5], v4 offset1:1
	v_mad_u64_u32 v[14:15], s[20:21], v15, s1, v[14:15]
	v_mov_b32_e32 v13, v14
	v_lshl_add_u64 v[12:13], v[12:13], 1, s[10:11]
	s_ashr_i32 s9, s8, 31
	v_lshl_add_u64 v[12:13], s[8:9], 1, v[12:13]
	v_lshl_add_u64 v[12:13], v[12:13], 0, v[0:1]
	s_waitcnt lgkmcnt(0)
	global_store_dwordx4 v[12:13], v[2:5], off
	s_andn2_b64 vcc, exec, s[26:27]
	s_cbranch_vccz .LBB0_834
